# peeled first K iteration with counted waits that skip the previous epilogue stores
# speedup vs baseline: 1.0087x; 1.0087x over previous
.LBB0_149:
	s_add_i32 s34, s19, -2
	s_add_u32 s92, s92, 0x80
	s_addc_u32 s93, s93, 0
	s_add_u32 s96, s94, 0x100
	v_mov_b32_e32 v0, 0
	s_addc_u32 s97, s95, 0
	s_mov_b32 s94, 0
	v_mov_b32_e32 v1, v0
	v_mov_b32_e32 v2, v0
	v_mov_b32_e32 v3, v0
	v_mov_b32_e32 v4, v0
	v_mov_b32_e32 v5, v0
	v_mov_b32_e32 v6, v0
	v_mov_b32_e32 v7, v0
	v_mov_b32_e32 v16, v0
	v_mov_b32_e32 v17, v0
	v_mov_b32_e32 v18, v0
	v_mov_b32_e32 v19, v0
	v_mov_b32_e32 v20, v0
	v_mov_b32_e32 v21, v0
	v_mov_b32_e32 v22, v0
	v_mov_b32_e32 v23, v0
	v_mov_b32_e32 v32, v0
	v_mov_b32_e32 v33, v0
	v_mov_b32_e32 v34, v0
	v_mov_b32_e32 v35, v0
	v_mov_b32_e32 v36, v0
	v_mov_b32_e32 v37, v0
	v_mov_b32_e32 v38, v0
	v_mov_b32_e32 v39, v0
	v_mov_b32_e32 v48, v0
	v_mov_b32_e32 v49, v0
	v_mov_b32_e32 v50, v0
	v_mov_b32_e32 v51, v0
	v_mov_b32_e32 v52, v0
	v_mov_b32_e32 v53, v0
	v_mov_b32_e32 v54, v0
	v_mov_b32_e32 v55, v0
	v_mov_b32_e32 v8, v0
	v_mov_b32_e32 v9, v0
	v_mov_b32_e32 v10, v0
	v_mov_b32_e32 v11, v0
	v_mov_b32_e32 v12, v0
	v_mov_b32_e32 v13, v0
	v_mov_b32_e32 v14, v0
	v_mov_b32_e32 v15, v0
	v_mov_b32_e32 v24, v0
	v_mov_b32_e32 v25, v0
	v_mov_b32_e32 v26, v0
	v_mov_b32_e32 v27, v0
	v_mov_b32_e32 v28, v0
	v_mov_b32_e32 v29, v0
	v_mov_b32_e32 v30, v0
	v_mov_b32_e32 v31, v0
	v_mov_b32_e32 v40, v0
	v_mov_b32_e32 v41, v0
	v_mov_b32_e32 v42, v0
	v_mov_b32_e32 v43, v0
	v_mov_b32_e32 v44, v0
	v_mov_b32_e32 v45, v0
	v_mov_b32_e32 v46, v0
	v_mov_b32_e32 v47, v0
	v_mov_b32_e32 v56, v0
	v_mov_b32_e32 v57, v0
	v_mov_b32_e32 v58, v0
	v_mov_b32_e32 v59, v0
	v_mov_b32_e32 v60, v0
	v_mov_b32_e32 v61, v0
	v_mov_b32_e32 v62, v0
	v_mov_b32_e32 v63, v0
	v_mov_b32_e32 v64, v0
	v_mov_b32_e32 v65, v0
	v_mov_b32_e32 v66, v0
	v_mov_b32_e32 v67, v0
	v_mov_b32_e32 v68, v0
	v_mov_b32_e32 v69, v0
	v_mov_b32_e32 v70, v0
	v_mov_b32_e32 v71, v0
	v_mov_b32_e32 v80, v0
	v_mov_b32_e32 v81, v0
	v_mov_b32_e32 v82, v0
	v_mov_b32_e32 v83, v0
	v_mov_b32_e32 v84, v0
	v_mov_b32_e32 v85, v0
	v_mov_b32_e32 v86, v0
	v_mov_b32_e32 v87, v0
	v_mov_b32_e32 v96, v0
	v_mov_b32_e32 v97, v0
	v_mov_b32_e32 v98, v0
	v_mov_b32_e32 v99, v0
	v_mov_b32_e32 v100, v0
	v_mov_b32_e32 v101, v0
	v_mov_b32_e32 v102, v0
	v_mov_b32_e32 v103, v0
	v_mov_b32_e32 v112, v0
	v_mov_b32_e32 v113, v0
	v_mov_b32_e32 v114, v0
	v_mov_b32_e32 v115, v0
	v_mov_b32_e32 v116, v0
	v_mov_b32_e32 v117, v0
	v_mov_b32_e32 v118, v0
	v_mov_b32_e32 v119, v0
	v_mov_b32_e32 v72, v0
	v_mov_b32_e32 v73, v0
	v_mov_b32_e32 v74, v0
	v_mov_b32_e32 v75, v0
	v_mov_b32_e32 v76, v0
	v_mov_b32_e32 v77, v0
	v_mov_b32_e32 v78, v0
	v_mov_b32_e32 v79, v0
	v_mov_b32_e32 v88, v0
	v_mov_b32_e32 v89, v0
	v_mov_b32_e32 v90, v0
	v_mov_b32_e32 v91, v0
	v_mov_b32_e32 v92, v0
	v_mov_b32_e32 v93, v0
	v_mov_b32_e32 v94, v0
	v_mov_b32_e32 v95, v0
	v_mov_b32_e32 v104, v0
	v_mov_b32_e32 v105, v0
	v_mov_b32_e32 v106, v0
	v_mov_b32_e32 v107, v0
	v_mov_b32_e32 v108, v0
	v_mov_b32_e32 v109, v0
	v_mov_b32_e32 v110, v0
	v_mov_b32_e32 v111, v0
	v_mov_b32_e32 v120, v0
	v_mov_b32_e32 v121, v0
	v_mov_b32_e32 v122, v0
	v_mov_b32_e32 v123, v0
	v_mov_b32_e32 v124, v0
	v_mov_b32_e32 v125, v0
	v_mov_b32_e32 v126, v0
	v_mov_b32_e32 v127, v0
	s_cmp_lt_u32 s59, 2
	s_cbranch_scc1 .LBB0_150
	s_add_i32 vcc_lo, s94, 2
	s_add_u32 s82, s92, 0x80
	s_addc_u32 s83, s93, 0
	s_add_i32 vcc_hi, 0, 0x10000
	s_cmp_eq_u32 s34, s94
	s_cselect_b32 s95, s89, s83
	s_cselect_b32 s94, s88, s82
	v_add_u32_e32 v136, vcc_hi, v176
	s_cselect_b32 s83, s91, s97
	s_cselect_b32 s82, s90, s96
	s_add_i32 s7, 0, 0x14000
	s_waitcnt lgkmcnt(0)
	ds_read_b128 v[128:131], v136
	ds_read_b128 v[132:135], v136 offset:1024
	ds_read_b128 v[152:155], v136 offset:2048
	ds_read_b128 v[156:159], v136 offset:3072
	v_add_u32_e32 v136, s7, v176
	ds_read_b128 v[180:183], v136
	ds_read_b128 v[184:187], v136 offset:1024
	ds_read_b128 v[188:191], v136 offset:2048
	ds_read_b128 v[192:195], v136 offset:3072
	v_lshl_add_u64 v[160:161], s[92:93], 0, v[148:149]
	s_add_i32 m0, s52, 0xc000
	ds_read_b128 v[196:199], v178
	ds_read_b128 v[200:203], v178 offset:1024
	ds_read_b128 v[204:207], v178 offset:2048
	ds_read_b128 v[208:211], v178 offset:3072
	ds_read_b128 v[212:215], v178 offset:4096
	ds_read_b128 v[216:219], v178 offset:5120
	ds_read_b128 v[220:223], v178 offset:6144
	ds_read_b128 v[224:227], v178 offset:7168
	global_load_lds_dwordx4 v[160:161], off
	v_lshl_add_u64 v[160:161], s[92:93], 0, v[150:151]
	s_add_i32 m0, s52, 0xe000
	s_nop 0
	global_load_lds_dwordx4 v[160:161], off
	s_waitcnt vmcnt(24)
	s_waitcnt lgkmcnt(0)
	s_barrier
	s_setprio 1
	s_waitcnt lgkmcnt(0)
	v_mfma_f32_16x16x32_bf16 v[124:127], v[128:131], v[196:199], v[124:127]
	v_mfma_f32_16x16x32_bf16 v[120:123], v[152:155], v[196:199], v[120:123]
	v_mfma_f32_16x16x32_bf16 v[108:111], v[128:131], v[204:207], v[108:111]
	v_mfma_f32_16x16x32_bf16 v[104:107], v[152:155], v[204:207], v[104:107]
	v_mfma_f32_16x16x32_bf16 v[92:95], v[128:131], v[212:215], v[92:95]
	v_mfma_f32_16x16x32_bf16 v[88:91], v[152:155], v[212:215], v[88:91]
	v_mfma_f32_16x16x32_bf16 v[76:79], v[128:131], v[220:223], v[76:79]
	v_mfma_f32_16x16x32_bf16 v[72:75], v[152:155], v[220:223], v[72:75]
	v_mfma_f32_16x16x32_bf16 v[124:127], v[132:135], v[200:203], v[124:127]
	v_mfma_f32_16x16x32_bf16 v[120:123], v[156:159], v[200:203], v[120:123]
	v_mfma_f32_16x16x32_bf16 v[108:111], v[132:135], v[208:211], v[108:111]
	v_mfma_f32_16x16x32_bf16 v[104:107], v[156:159], v[208:211], v[104:107]
	v_mfma_f32_16x16x32_bf16 v[92:95], v[132:135], v[216:219], v[92:95]
	v_mfma_f32_16x16x32_bf16 v[88:91], v[156:159], v[216:219], v[88:91]
	v_mfma_f32_16x16x32_bf16 v[76:79], v[132:135], v[224:227], v[76:79]
	v_mfma_f32_16x16x32_bf16 v[72:75], v[156:159], v[224:227], v[72:75]
	s_setprio 0
	s_setprio 1
	v_mfma_f32_16x16x32_bf16 v[116:119], v[180:183], v[196:199], v[116:119]
	v_mfma_f32_16x16x32_bf16 v[112:115], v[188:191], v[196:199], v[112:115]
	v_mfma_f32_16x16x32_bf16 v[100:103], v[180:183], v[204:207], v[100:103]
	v_mfma_f32_16x16x32_bf16 v[96:99], v[188:191], v[204:207], v[96:99]
	v_mfma_f32_16x16x32_bf16 v[84:87], v[180:183], v[212:215], v[84:87]
	v_mfma_f32_16x16x32_bf16 v[80:83], v[188:191], v[212:215], v[80:83]
	v_mfma_f32_16x16x32_bf16 v[68:71], v[180:183], v[220:223], v[68:71]
	v_mfma_f32_16x16x32_bf16 v[64:67], v[188:191], v[220:223], v[64:67]
	v_mfma_f32_16x16x32_bf16 v[116:119], v[184:187], v[200:203], v[116:119]
	v_mfma_f32_16x16x32_bf16 v[112:115], v[192:195], v[200:203], v[112:115]
	v_mfma_f32_16x16x32_bf16 v[100:103], v[184:187], v[208:211], v[100:103]
	v_mfma_f32_16x16x32_bf16 v[96:99], v[192:195], v[208:211], v[96:99]
	v_mfma_f32_16x16x32_bf16 v[84:87], v[184:187], v[216:219], v[84:87]
	v_mfma_f32_16x16x32_bf16 v[80:83], v[192:195], v[216:219], v[80:83]
	v_mfma_f32_16x16x32_bf16 v[68:71], v[184:187], v[224:227], v[68:71]
	v_mfma_f32_16x16x32_bf16 v[64:67], v[192:195], v[224:227], v[64:67]
	s_setprio 0
	s_barrier
	s_add_i32 vcc_hi, vcc_hi, s51
	v_lshl_add_u64 v[160:161], s[82:83], 0, v[140:141]
	s_mov_b32 m0, vcc_hi
	ds_read_b128 v[196:199], v178 offset:16384
	ds_read_b128 v[200:203], v178 offset:17408
	ds_read_b128 v[204:207], v178 offset:18432
	ds_read_b128 v[208:211], v178 offset:19456
	ds_read_b128 v[212:215], v178 offset:20480
	ds_read_b128 v[216:219], v178 offset:21504
	ds_read_b128 v[220:223], v178 offset:22528
	ds_read_b128 v[224:227], v178 offset:23552
	global_load_lds_dwordx4 v[160:161], off
	s_add_i32 m0, vcc_hi, 0x2000
	v_lshl_add_u64 v[228:229], s[82:83], 0, v[144:145]
	s_add_u32 s82, s82, s2
	s_addc_u32 s83, s83, s3
	s_add_i32 s7, s7, s51
	global_load_lds_dwordx4 v[228:229], off
	v_lshl_add_u64 v[230:231], s[82:83], 0, v[140:141]
	s_mov_b32 m0, s7
	v_lshl_add_u64 v[232:233], s[82:83], 0, v[144:145]
	global_load_lds_dwordx4 v[230:231], off
	s_add_i32 m0, s7, 0x2000
	v_lshl_add_u64 v[234:235], s[94:95], 0, v[138:139]
	global_load_lds_dwordx4 v[232:233], off
	s_mov_b32 m0, s52
	v_lshl_add_u64 v[236:237], s[94:95], 0, v[142:143]
	global_load_lds_dwordx4 v[234:235], off
	s_mov_b32 m0, s53
	s_nop 0
	global_load_lds_dwordx4 v[236:237], off
	s_waitcnt vmcnt(24)
	s_waitcnt lgkmcnt(0)
	s_barrier
	s_setprio 1
	s_waitcnt lgkmcnt(0)
	v_mfma_f32_16x16x32_bf16 v[60:63], v[128:131], v[196:199], v[60:63]
	v_mfma_f32_16x16x32_bf16 v[56:59], v[152:155], v[196:199], v[56:59]
	v_mfma_f32_16x16x32_bf16 v[44:47], v[128:131], v[204:207], v[44:47]
	v_mfma_f32_16x16x32_bf16 v[40:43], v[152:155], v[204:207], v[40:43]
	v_mfma_f32_16x16x32_bf16 v[28:31], v[128:131], v[212:215], v[28:31]
	v_mfma_f32_16x16x32_bf16 v[24:27], v[152:155], v[212:215], v[24:27]
	v_mfma_f32_16x16x32_bf16 v[12:15], v[128:131], v[220:223], v[12:15]
	v_mfma_f32_16x16x32_bf16 v[8:11], v[152:155], v[220:223], v[8:11]
	v_mfma_f32_16x16x32_bf16 v[60:63], v[132:135], v[200:203], v[60:63]
	v_mfma_f32_16x16x32_bf16 v[56:59], v[156:159], v[200:203], v[56:59]
	v_mfma_f32_16x16x32_bf16 v[44:47], v[132:135], v[208:211], v[44:47]
	v_mfma_f32_16x16x32_bf16 v[40:43], v[156:159], v[208:211], v[40:43]
	v_mfma_f32_16x16x32_bf16 v[28:31], v[132:135], v[216:219], v[28:31]
	v_mfma_f32_16x16x32_bf16 v[24:27], v[156:159], v[216:219], v[24:27]
	v_mfma_f32_16x16x32_bf16 v[12:15], v[132:135], v[224:227], v[12:15]
	v_mfma_f32_16x16x32_bf16 v[8:11], v[156:159], v[224:227], v[8:11]
	s_setprio 0
	s_setprio 1
	v_mfma_f32_16x16x32_bf16 v[52:55], v[180:183], v[196:199], v[52:55]
	v_mfma_f32_16x16x32_bf16 v[48:51], v[188:191], v[196:199], v[48:51]
	v_mfma_f32_16x16x32_bf16 v[36:39], v[180:183], v[204:207], v[36:39]
	v_mfma_f32_16x16x32_bf16 v[32:35], v[188:191], v[204:207], v[32:35]
	v_mfma_f32_16x16x32_bf16 v[20:23], v[180:183], v[212:215], v[20:23]
	v_mfma_f32_16x16x32_bf16 v[16:19], v[188:191], v[212:215], v[16:19]
	v_mfma_f32_16x16x32_bf16 v[4:7], v[180:183], v[220:223], v[4:7]
	v_mfma_f32_16x16x32_bf16 v[0:3], v[188:191], v[220:223], v[0:3]
	v_mfma_f32_16x16x32_bf16 v[52:55], v[184:187], v[200:203], v[52:55]
	v_mfma_f32_16x16x32_bf16 v[48:51], v[192:195], v[200:203], v[48:51]
	v_mfma_f32_16x16x32_bf16 v[36:39], v[184:187], v[208:211], v[36:39]
	v_mfma_f32_16x16x32_bf16 v[32:35], v[192:195], v[208:211], v[32:35]
	v_mfma_f32_16x16x32_bf16 v[20:23], v[184:187], v[216:219], v[20:23]
	v_mfma_f32_16x16x32_bf16 v[16:19], v[192:195], v[216:219], v[16:19]
	v_mfma_f32_16x16x32_bf16 v[4:7], v[184:187], v[224:227], v[4:7]
	v_mfma_f32_16x16x32_bf16 v[0:3], v[192:195], v[224:227], v[0:3]
	s_setprio 0
	s_barrier
	s_add_i32 s7, 0, 0x18000
	v_add_u32_e32 v136, s7, v176
	s_add_i32 vcc_hi, 0, 0x1c000
	ds_read_b128 v[128:131], v136
	ds_read_b128 v[132:135], v136 offset:1024
	ds_read_b128 v[152:155], v136 offset:2048
	ds_read_b128 v[156:159], v136 offset:3072
	v_add_u32_e32 v136, vcc_hi, v176
	ds_read_b128 v[180:183], v136
	ds_read_b128 v[184:187], v136 offset:1024
	ds_read_b128 v[188:191], v136 offset:2048
	ds_read_b128 v[192:195], v136 offset:3072
	s_add_u32 s82, s94, s2
	s_addc_u32 s83, s95, s3
	s_mov_b32 m0, s54
	v_lshl_add_u64 v[238:239], s[82:83], 0, v[138:139]
	ds_read_b128 v[196:199], v178 offset:32768
	ds_read_b128 v[200:203], v178 offset:33792
	ds_read_b128 v[204:207], v178 offset:34816
	ds_read_b128 v[208:211], v178 offset:35840
	ds_read_b128 v[212:215], v178 offset:36864
	ds_read_b128 v[216:219], v178 offset:37888
	ds_read_b128 v[220:223], v178 offset:38912
	ds_read_b128 v[224:227], v178 offset:39936
	global_load_lds_dwordx4 v[238:239], off
	v_lshl_add_u64 v[238:239], s[82:83], 0, v[142:143]
	s_mov_b32 m0, s55
	s_nop 0
	global_load_lds_dwordx4 v[238:239], off
	s_waitcnt vmcnt(8)
	s_waitcnt lgkmcnt(0)
	s_barrier
	s_setprio 1
	s_waitcnt lgkmcnt(0)
	v_mfma_f32_16x16x32_bf16 v[124:127], v[128:131], v[196:199], v[124:127]
	v_mfma_f32_16x16x32_bf16 v[120:123], v[152:155], v[196:199], v[120:123]
	v_mfma_f32_16x16x32_bf16 v[108:111], v[128:131], v[204:207], v[108:111]
	v_mfma_f32_16x16x32_bf16 v[104:107], v[152:155], v[204:207], v[104:107]
	v_mfma_f32_16x16x32_bf16 v[92:95], v[128:131], v[212:215], v[92:95]
	v_mfma_f32_16x16x32_bf16 v[88:91], v[152:155], v[212:215], v[88:91]
	v_mfma_f32_16x16x32_bf16 v[76:79], v[128:131], v[220:223], v[76:79]
	v_mfma_f32_16x16x32_bf16 v[72:75], v[152:155], v[220:223], v[72:75]
	v_mfma_f32_16x16x32_bf16 v[124:127], v[132:135], v[200:203], v[124:127]
	v_mfma_f32_16x16x32_bf16 v[120:123], v[156:159], v[200:203], v[120:123]
	v_mfma_f32_16x16x32_bf16 v[108:111], v[132:135], v[208:211], v[108:111]
	v_mfma_f32_16x16x32_bf16 v[104:107], v[156:159], v[208:211], v[104:107]
	v_mfma_f32_16x16x32_bf16 v[92:95], v[132:135], v[216:219], v[92:95]
	v_mfma_f32_16x16x32_bf16 v[88:91], v[156:159], v[216:219], v[88:91]
	v_mfma_f32_16x16x32_bf16 v[76:79], v[132:135], v[224:227], v[76:79]
	v_mfma_f32_16x16x32_bf16 v[72:75], v[156:159], v[224:227], v[72:75]
	s_setprio 0
	s_setprio 1
	v_mfma_f32_16x16x32_bf16 v[116:119], v[180:183], v[196:199], v[116:119]
	v_mfma_f32_16x16x32_bf16 v[112:115], v[188:191], v[196:199], v[112:115]
	v_mfma_f32_16x16x32_bf16 v[100:103], v[180:183], v[204:207], v[100:103]
	v_mfma_f32_16x16x32_bf16 v[96:99], v[188:191], v[204:207], v[96:99]
	v_mfma_f32_16x16x32_bf16 v[84:87], v[180:183], v[212:215], v[84:87]
	v_mfma_f32_16x16x32_bf16 v[80:83], v[188:191], v[212:215], v[80:83]
	v_mfma_f32_16x16x32_bf16 v[68:71], v[180:183], v[220:223], v[68:71]
	v_mfma_f32_16x16x32_bf16 v[64:67], v[188:191], v[220:223], v[64:67]
	v_mfma_f32_16x16x32_bf16 v[116:119], v[184:187], v[200:203], v[116:119]
	v_mfma_f32_16x16x32_bf16 v[112:115], v[192:195], v[200:203], v[112:115]
	v_mfma_f32_16x16x32_bf16 v[100:103], v[184:187], v[208:211], v[100:103]
	v_mfma_f32_16x16x32_bf16 v[96:99], v[192:195], v[208:211], v[96:99]
	v_mfma_f32_16x16x32_bf16 v[84:87], v[184:187], v[216:219], v[84:87]
	v_mfma_f32_16x16x32_bf16 v[80:83], v[192:195], v[216:219], v[80:83]
	v_mfma_f32_16x16x32_bf16 v[68:71], v[184:187], v[224:227], v[68:71]
	v_mfma_f32_16x16x32_bf16 v[64:67], v[192:195], v[224:227], v[64:67]
	s_setprio 0
	s_barrier
	s_add_i32 s7, s7, s51
	v_lshl_add_u64 v[160:161], v[160:161], 0, s[26:27]
	s_mov_b32 m0, s7
	ds_read_b128 v[196:199], v178 offset:49152
	ds_read_b128 v[200:203], v178 offset:50176
	ds_read_b128 v[204:207], v178 offset:51200
	ds_read_b128 v[208:211], v178 offset:52224
	ds_read_b128 v[212:215], v178 offset:53248
	ds_read_b128 v[216:219], v178 offset:54272
	ds_read_b128 v[220:223], v178 offset:55296
	ds_read_b128 v[224:227], v178 offset:56320
	global_load_lds_dwordx4 v[160:161], off
	v_lshl_add_u64 v[160:161], v[228:229], 0, s[26:27]
	s_add_i32 m0, s7, 0x2000
	s_add_i32 s7, vcc_hi, s51
	global_load_lds_dwordx4 v[160:161], off
	v_lshl_add_u64 v[160:161], v[230:231], 0, s[26:27]
	s_mov_b32 m0, s7
	s_nop 0
	global_load_lds_dwordx4 v[160:161], off
	v_lshl_add_u64 v[160:161], v[232:233], 0, s[26:27]
	s_add_i32 m0, s7, 0x2000
	s_nop 0
	global_load_lds_dwordx4 v[160:161], off
	v_lshl_add_u64 v[160:161], v[234:235], 0, s[26:27]
	s_mov_b32 m0, s57
	s_nop 0
	global_load_lds_dwordx4 v[160:161], off
	v_lshl_add_u64 v[160:161], v[236:237], 0, s[26:27]
	s_mov_b32 m0, s58
	s_nop 0
	global_load_lds_dwordx4 v[160:161], off
	s_waitcnt vmcnt(8)
	s_waitcnt lgkmcnt(0)
	s_barrier
	s_setprio 1
	s_waitcnt lgkmcnt(0)
	v_mfma_f32_16x16x32_bf16 v[60:63], v[128:131], v[196:199], v[60:63]
	v_mfma_f32_16x16x32_bf16 v[56:59], v[152:155], v[196:199], v[56:59]
	v_mfma_f32_16x16x32_bf16 v[44:47], v[128:131], v[204:207], v[44:47]
	v_mfma_f32_16x16x32_bf16 v[40:43], v[152:155], v[204:207], v[40:43]
	v_mfma_f32_16x16x32_bf16 v[28:31], v[128:131], v[212:215], v[28:31]
	v_mfma_f32_16x16x32_bf16 v[24:27], v[152:155], v[212:215], v[24:27]
	v_mfma_f32_16x16x32_bf16 v[12:15], v[128:131], v[220:223], v[12:15]
	v_mfma_f32_16x16x32_bf16 v[8:11], v[152:155], v[220:223], v[8:11]
	v_mfma_f32_16x16x32_bf16 v[60:63], v[132:135], v[200:203], v[60:63]
	v_mfma_f32_16x16x32_bf16 v[56:59], v[156:159], v[200:203], v[56:59]
	v_mfma_f32_16x16x32_bf16 v[44:47], v[132:135], v[208:211], v[44:47]
	v_mfma_f32_16x16x32_bf16 v[40:43], v[156:159], v[208:211], v[40:43]
	v_mfma_f32_16x16x32_bf16 v[28:31], v[132:135], v[216:219], v[28:31]
	v_mfma_f32_16x16x32_bf16 v[24:27], v[156:159], v[216:219], v[24:27]
	v_mfma_f32_16x16x32_bf16 v[12:15], v[132:135], v[224:227], v[12:15]
	v_mfma_f32_16x16x32_bf16 v[8:11], v[156:159], v[224:227], v[8:11]
	s_setprio 0
	s_setprio 1
	v_mfma_f32_16x16x32_bf16 v[52:55], v[180:183], v[196:199], v[52:55]
	v_mfma_f32_16x16x32_bf16 v[48:51], v[188:191], v[196:199], v[48:51]
	v_mfma_f32_16x16x32_bf16 v[36:39], v[180:183], v[204:207], v[36:39]
	v_mfma_f32_16x16x32_bf16 v[32:35], v[188:191], v[204:207], v[32:35]
	v_mfma_f32_16x16x32_bf16 v[20:23], v[180:183], v[212:215], v[20:23]
	v_mfma_f32_16x16x32_bf16 v[16:19], v[188:191], v[212:215], v[16:19]
	v_mfma_f32_16x16x32_bf16 v[4:7], v[180:183], v[220:223], v[4:7]
	v_mfma_f32_16x16x32_bf16 v[0:3], v[188:191], v[220:223], v[0:3]
	v_mfma_f32_16x16x32_bf16 v[52:55], v[184:187], v[200:203], v[52:55]
	v_mfma_f32_16x16x32_bf16 v[48:51], v[192:195], v[200:203], v[48:51]
	v_mfma_f32_16x16x32_bf16 v[36:39], v[184:187], v[208:211], v[36:39]
	v_mfma_f32_16x16x32_bf16 v[32:35], v[192:195], v[208:211], v[32:35]
	v_mfma_f32_16x16x32_bf16 v[20:23], v[184:187], v[216:219], v[20:23]
	v_mfma_f32_16x16x32_bf16 v[16:19], v[192:195], v[216:219], v[16:19]
	v_mfma_f32_16x16x32_bf16 v[4:7], v[184:187], v[224:227], v[4:7]
	v_mfma_f32_16x16x32_bf16 v[0:3], v[192:195], v[224:227], v[0:3]
	s_setprio 0
	s_barrier
	s_add_u32 s92, s92, 0x100
	s_addc_u32 s93, s93, 0
	s_add_u32 s96, s96, 0x100
	s_addc_u32 s97, s97, 0
	s_cmp_ge_u32 vcc_lo, s19
	s_mov_b32 s94, vcc_lo
	s_cbranch_scc0 .LBB0_150
	s_branch .Lkloop_done

.Lkloop_done:
	s_and_b64 vcc, exec, s[80:81]
	s_cbranch_vccz .LBB0_153
	s_barrier
